# DSA: 14 more redundant canonicalising self-max before max replaced by s_nop 0
# baseline (speedup 1.0000x reference)
.LBB0_256:
	s_or_b64 exec, exec, s[34:35]
	s_nop 4
	s_nop 0
	s_nop 0
	v_max_f32_e32 v130, v130, v131
	v_max_f32_e32 v131, v133, v133
	s_nop 0
	v_max_f32_e32 v131, v132, v131
	s_add_i32 s34, s43, -1
	s_cmp_ge_u32 s34, s42
	v_max3_f32 v204, v204, v130, v131
	s_cbranch_scc0 .LBB0_259
	s_cmp_ge_u32 s43, s42
	s_cbranch_scc0 .LBB0_262

.LBB0_261:
	s_or_b64 exec, exec, s[34:35]
	s_nop 4
	s_nop 0
	s_nop 0
	v_max_f32_e32 v66, v66, v67
	v_max_f32_e32 v67, v69, v69
	s_nop 0
	v_max_f32_e32 v67, v68, v67
	v_max3_f32 v204, v204, v66, v67
	s_cmp_ge_u32 s43, s42
	s_cbranch_scc1 .LBB0_258

.LBB0_264:
	s_or_b64 exec, exec, s[34:35]
	s_nop 4
	s_nop 0
	s_nop 0
	v_max_f32_e32 v34, v34, v35
	v_max_f32_e32 v35, v37, v37
	s_nop 0
	v_max_f32_e32 v35, v36, v35
	v_max3_f32 v204, v204, v34, v35
	s_add_i32 s34, s43, 1
	s_cmp_ge_u32 s34, s42
	s_cbranch_scc1 .LBB0_268

.LBB0_267:
	s_or_b64 exec, exec, s[34:35]
	s_nop 4
	s_nop 0
	s_nop 0
	v_max_f32_e32 v18, v18, v19
	v_max_f32_e32 v19, v21, v21
	s_nop 0
	v_max_f32_e32 v19, v20, v19
	v_max3_f32 v204, v204, v18, v19

.LBB0_270:
	s_waitcnt vmcnt(0)
	v_and_b32_e32 v98, 64, v198
	v_xor_b32_e32 v2, 16, v198
	v_add_u32_e32 v14, 64, v98
	v_cmp_lt_i32_e32 vcc, v2, v14
	v_max_f32_e32 v3, v204, v204
	v_mov_b32_e32 v15, 0
	v_cndmask_b32_e32 v2, v198, v2, vcc
	v_lshlrev_b32_e32 v99, 2, v2
	ds_bpermute_b32 v2, v99, v204
	s_waitcnt lgkmcnt(0)
	s_nop 0
	v_max_f32_e32 v2, v3, v2
	v_xor_b32_e32 v3, 32, v198
	v_cmp_lt_i32_e32 vcc, v3, v14
	s_nop 1
	v_cndmask_b32_e32 v3, v198, v3, vcc
	v_lshlrev_b32_e32 v100, 2, v3
	ds_bpermute_b32 v3, v100, v2
	v_cmp_ge_u32_e32 vcc, s50, v182
	s_waitcnt lgkmcnt(0)
	s_nop 0
	v_max_f32_e32 v2, v2, v3
	v_or_b32_e32 v3, v98, v181
	v_lshlrev_b32_e32 v3, 2, v3
	ds_bpermute_b32 v2, v3, v2
	v_mov_b32_e32 v15, 0
	v_mov_b32_e32 v4, v182
	s_movk_i32 s42, 4
	s_waitcnt lgkmcnt(0)
	v_mov_b32_e32 v3, v203
